# v22: v21 + GEMM EpiScale epilogues: second half's row-statistic loads issued with the first half's (free VGPRs), no vmcnt(0) store drain in the middle of the epilogue
# speedup vs baseline: 1.0031x; 1.0022x over previous
.LBB0_471:
	v_lshl_add_u32 v144, s44, 8, v152
	v_ashrrev_i32_e32 v145, 31, v144
	s_and_b64 vcc, exec, s[50:51]
	v_or_b32_e32 v150, 16, v144
	v_or_b32_e32 v148, 32, v144
	v_or_b32_e32 v146, 48, v144
	s_mov_b32 s53, 0x800000
	s_cbranch_vccz .LBB0_480
	v_ashrrev_i32_e32 v151, 31, v150
	v_lshlrev_b64 v[142:143], 6, v[144:145]
	v_lshlrev_b64 v[156:157], 6, v[150:151]
	v_lshl_add_u64 v[142:143], v[136:137], 0, v[142:143]
	v_lshl_add_u64 v[160:161], v[136:137], 0, v[156:157]
	v_ashrrev_i32_e32 v149, 31, v148
	v_ashrrev_i32_e32 v147, 31, v146
	global_load_dwordx4 v[156:159], v[142:143], off
	s_nop 0
	global_load_dwordx4 v[160:163], v[160:161], off
	v_lshlrev_b64 v[142:143], 6, v[148:149]
	v_lshlrev_b64 v[164:165], 6, v[146:147]
	v_lshl_add_u64 v[142:143], v[136:137], 0, v[142:143]
	v_lshl_add_u64 v[168:169], v[136:137], 0, v[164:165]
	global_load_dwordx4 v[164:167], v[142:143], off
	s_nop 0
	global_load_dwordx4 v[168:171], v[168:169], off
	v_add_u32_e32 v192, 0x80, v144
	v_ashrrev_i32_e32 v193, 31, v192
	v_lshlrev_b64 v[192:193], 6, v[192:193]
	v_lshl_add_u64 v[192:193], v[136:137], 0, v[192:193]
	global_load_dwordx4 v[176:179], v[192:193], off
	global_load_dwordx4 v[180:183], v[192:193], off offset:1024
	global_load_dwordx4 v[184:187], v[192:193], off offset:2048
	global_load_dwordx4 v[188:191], v[192:193], off offset:3072
	v_cmp_lt_i32_e32 vcc, v218, v213
	s_waitcnt vmcnt(0)
	v_mov_b32_e32 v143, v160
	v_mov_b32_e32 v160, v157
	v_cndmask_b32_e32 v142, v211, v218, vcc
	v_cmp_lt_i32_e32 vcc, v219, v213
	v_lshlrev_b32_e32 v145, 2, v142
	v_mov_b32_e32 v157, v162
	v_cndmask_b32_e32 v142, v211, v219, vcc
	v_lshlrev_b32_e32 v172, 2, v142
	v_mov_b32_e32 v142, v156
	v_mov_b32_e32 v156, v158
	v_mov_b32_e32 v162, v159
	v_pk_add_f32 v[142:143], v[142:143], v[160:161]
	v_pk_add_f32 v[156:157], v[156:157], v[162:163]
	v_add_f32_e32 v160, v164, v165
	v_pk_add_f32 v[142:143], v[142:143], v[156:157]
	ds_bpermute_b32 v156, v145, v142
	ds_bpermute_b32 v157, v145, v143
	v_mov_b32_e32 v164, v169
	v_mov_b32_e32 v165, v170
	v_mov_b32_e32 v169, v171
	v_pk_add_f32 v[164:165], v[164:165], v[168:169]
	s_waitcnt lgkmcnt(0)
	v_pk_add_f32 v[142:143], v[142:143], v[156:157]
	ds_bpermute_b32 v156, v172, v142
	ds_bpermute_b32 v157, v172, v143
	v_add_f32_e32 v162, v166, v167
	v_mov_b32_e32 v161, v164
	v_mov_b32_e32 v163, v165
	v_pk_add_f32 v[160:161], v[160:161], v[162:163]
	ds_bpermute_b32 v162, v145, v160
	ds_bpermute_b32 v163, v145, v161
	s_mov_b32 s44, 0x358637bd
	s_waitcnt lgkmcnt(2)
	v_pk_add_f32 v[142:143], v[142:143], v[156:157]
	v_mov_b64_e32 v[158:159], s[44:45]
	s_mov_b32 s62, 0x3a800000
	v_pk_fma_f32 v[142:143], v[142:143], s[62:63], v[158:159] op_sel_hi:[1,0,0]
	s_waitcnt lgkmcnt(0)
	v_pk_add_f32 v[160:161], v[160:161], v[162:163]
	v_mul_f32_e32 v156, 0x4b800000, v142
	v_cmp_gt_f32_e64 s[44:45], s53, v142
	v_cmp_gt_f32_e32 vcc, s53, v143
	ds_bpermute_b32 v162, v172, v160
	v_cndmask_b32_e64 v142, v142, v156, s[44:45]
	v_mul_f32_e32 v156, 0x4b800000, v143
	ds_bpermute_b32 v163, v172, v161
	v_cndmask_b32_e32 v143, v143, v156, vcc
	v_rsq_f32_e32 v142, v142
	v_rsq_f32_e32 v143, v143
	s_mov_b32 s60, 0x45800000
	s_waitcnt lgkmcnt(0)
	v_pk_add_f32 v[160:161], v[160:161], v[162:163]
	v_pk_mul_f32 v[156:157], v[142:143], s[60:61] op_sel_hi:[1,0]
	v_pk_fma_f32 v[158:159], v[160:161], s[62:63], v[158:159] op_sel_hi:[1,0,0]
	v_cndmask_b32_e64 v142, v142, v156, s[44:45]
	v_cndmask_b32_e32 v156, v143, v157, vcc
	v_mul_f32_e32 v143, 0x4b800000, v158
	v_cmp_gt_f32_e64 s[44:45], s53, v158
	v_cmp_gt_f32_e32 vcc, s53, v159
	s_nop 0
	v_cndmask_b32_e64 v143, v158, v143, s[44:45]
	v_rsq_f32_e32 v158, v143
	v_mul_f32_e32 v143, 0x4b800000, v159
	v_cndmask_b32_e32 v143, v159, v143, vcc
	v_rsq_f32_e32 v159, v143
	s_nop 0
	v_pk_mul_f32 v[160:161], v[158:159], s[60:61] op_sel_hi:[1,0]
	s_nop 0
	v_cndmask_b32_e64 v158, v158, v160, s[44:45]
	v_cndmask_b32_e32 v157, v159, v161, vcc
	v_mov_b32_e32 v238, v195
	s_cbranch_execnz .LBB0_474

.LBB0_474:
	s_cmp_ge_i32 s67, s9
	s_cselect_b64 s[44:45], -1, 0
	s_cmp_lt_i32 s67, s5
	s_cselect_b64 s[60:61], -1, 0
	v_mov_b32_e32 v143, s4
	s_and_b64 vcc, s[44:45], s[60:61]
	v_lshl_or_b32 v160, s67, 8, v154
	v_cndmask_b32_e32 v145, 1.0, v143, vcc
	v_ashrrev_i32_e32 v161, 31, v160
	v_mul_f32_e32 v162, v145, v142
	v_mad_i64_i32 v[142:143], s[44:45], v144, s1, 0
	v_lshl_add_u64 v[164:165], v[142:143], 1, s[16:17]
	v_lshlrev_b64 v[142:143], 1, v[160:161]
	v_lshl_add_u64 v[160:161], v[164:165], 0, v[142:143]
	v_pk_mul_f32 v[128:129], v[128:129], v[162:163] op_sel_hi:[1,0]
	v_pk_mul_f32 v[126:127], v[126:127], v[162:163] op_sel_hi:[1,0]
	v_pk_mul_f32 v[164:165], v[124:125], v[162:163] op_sel_hi:[1,0]
	v_pk_mul_f32 v[124:125], v[122:123], v[162:163] op_sel_hi:[1,0]
	v_cvt_pk_bf16_f32 v122, v126, v127
	v_cvt_pk_bf16_f32 v123, v128, v129
	v_cvt_pk_bf16_f32 v124, v124, v125
	v_cvt_pk_bf16_f32 v125, v164, v165
	global_store_dwordx4 v[160:161], v[122:125], off
	v_pk_mul_f32 v[120:121], v[120:121], v[162:163] op_sel_hi:[1,0]
	v_pk_mul_f32 v[118:119], v[118:119], v[162:163] op_sel_hi:[1,0]
	v_pk_mul_f32 v[122:123], v[112:113], v[162:163] op_sel_hi:[1,0]
	v_pk_mul_f32 v[112:113], v[110:111], v[162:163] op_sel_hi:[1,0]
	v_cvt_pk_bf16_f32 v110, v118, v119
	v_cvt_pk_bf16_f32 v111, v120, v121
	v_cvt_pk_bf16_f32 v112, v112, v113
	v_cvt_pk_bf16_f32 v113, v122, v123
	global_store_dwordx4 v[160:161], v[110:113], off offset:256
	s_andn2_b64 vcc, exec, s[50:51]
	s_nop 0
	v_mad_u64_u32 v[112:113], s[44:45], v150, s1, 0
	v_mov_b32_e32 v118, v113
	v_mad_u64_u32 v[118:119], s[44:45], v151, s1, v[118:119]
	v_mul_f32_e32 v110, v145, v156
	v_mov_b32_e32 v113, v118
	v_lshl_add_u64 v[112:113], v[112:113], 1, s[16:17]
	v_pk_mul_f32 v[116:117], v[116:117], v[110:111] op_sel_hi:[1,0]
	v_pk_mul_f32 v[114:115], v[114:115], v[110:111] op_sel_hi:[1,0]
	v_pk_mul_f32 v[118:119], v[108:109], v[110:111] op_sel_hi:[1,0]
	v_pk_mul_f32 v[108:109], v[106:107], v[110:111] op_sel_hi:[1,0]
	v_lshl_add_u64 v[112:113], v[112:113], 0, v[142:143]
	v_cvt_pk_bf16_f32 v106, v114, v115
	v_cvt_pk_bf16_f32 v107, v116, v117
	v_cvt_pk_bf16_f32 v108, v108, v109
	v_cvt_pk_bf16_f32 v109, v118, v119
	global_store_dwordx4 v[112:113], v[106:109], off
	v_pk_mul_f32 v[104:105], v[104:105], v[110:111] op_sel_hi:[1,0]
	v_pk_mul_f32 v[102:103], v[102:103], v[110:111] op_sel_hi:[1,0]
	v_pk_mul_f32 v[106:107], v[96:97], v[110:111] op_sel_hi:[1,0]
	v_pk_mul_f32 v[96:97], v[94:95], v[110:111] op_sel_hi:[1,0]
	v_cvt_pk_bf16_f32 v94, v102, v103
	v_cvt_pk_bf16_f32 v95, v104, v105
	v_cvt_pk_bf16_f32 v96, v96, v97
	v_cvt_pk_bf16_f32 v97, v106, v107
	global_store_dwordx4 v[112:113], v[94:97], off offset:256
	s_nop 1
	v_mad_u64_u32 v[96:97], s[44:45], v148, s1, 0
	v_mov_b32_e32 v102, v97
	v_mad_u64_u32 v[102:103], s[44:45], v149, s1, v[102:103]
	v_mul_f32_e32 v94, v145, v158
	v_mov_b32_e32 v97, v102
	v_lshl_add_u64 v[96:97], v[96:97], 1, s[16:17]
	v_pk_mul_f32 v[100:101], v[100:101], v[94:95] op_sel_hi:[1,0]
	v_pk_mul_f32 v[98:99], v[98:99], v[94:95] op_sel_hi:[1,0]
	v_pk_mul_f32 v[102:103], v[92:93], v[94:95] op_sel_hi:[1,0]
	v_pk_mul_f32 v[92:93], v[90:91], v[94:95] op_sel_hi:[1,0]
	v_lshl_add_u64 v[96:97], v[96:97], 0, v[142:143]
	v_cvt_pk_bf16_f32 v90, v98, v99
	v_cvt_pk_bf16_f32 v91, v100, v101
	v_cvt_pk_bf16_f32 v92, v92, v93
	v_cvt_pk_bf16_f32 v93, v102, v103
	global_store_dwordx4 v[96:97], v[90:93], off
	v_pk_mul_f32 v[88:89], v[88:89], v[94:95] op_sel_hi:[1,0]
	v_pk_mul_f32 v[86:87], v[86:87], v[94:95] op_sel_hi:[1,0]
	v_pk_mul_f32 v[90:91], v[80:81], v[94:95] op_sel_hi:[1,0]
	v_pk_mul_f32 v[80:81], v[78:79], v[94:95] op_sel_hi:[1,0]
	v_cvt_pk_bf16_f32 v78, v86, v87
	v_cvt_pk_bf16_f32 v79, v88, v89
	v_cvt_pk_bf16_f32 v80, v80, v81
	v_cvt_pk_bf16_f32 v81, v90, v91
	global_store_dwordx4 v[96:97], v[78:81], off offset:256
	s_nop 1
	v_mad_u64_u32 v[80:81], s[44:45], v146, s1, 0
	v_mov_b32_e32 v86, v81
	v_mad_u64_u32 v[86:87], s[44:45], v147, s1, v[86:87]
	v_mul_f32_e32 v78, v145, v157
	v_mov_b32_e32 v81, v86
	v_lshl_add_u64 v[80:81], v[80:81], 1, s[16:17]
	v_pk_mul_f32 v[84:85], v[84:85], v[78:79] op_sel_hi:[1,0]
	v_pk_mul_f32 v[82:83], v[82:83], v[78:79] op_sel_hi:[1,0]
	v_pk_mul_f32 v[86:87], v[76:77], v[78:79] op_sel_hi:[1,0]
	v_pk_mul_f32 v[76:77], v[74:75], v[78:79] op_sel_hi:[1,0]
	v_lshl_add_u64 v[80:81], v[80:81], 0, v[142:143]
	v_cvt_pk_bf16_f32 v74, v82, v83
	v_cvt_pk_bf16_f32 v75, v84, v85
	v_cvt_pk_bf16_f32 v76, v76, v77
	v_cvt_pk_bf16_f32 v77, v86, v87
	global_store_dwordx4 v[80:81], v[74:77], off
	v_pk_mul_f32 v[72:73], v[72:73], v[78:79] op_sel_hi:[1,0]
	v_pk_mul_f32 v[70:71], v[70:71], v[78:79] op_sel_hi:[1,0]
	v_pk_mul_f32 v[74:75], v[68:69], v[78:79] op_sel_hi:[1,0]
	v_pk_mul_f32 v[68:69], v[66:67], v[78:79] op_sel_hi:[1,0]
	v_cvt_pk_bf16_f32 v66, v70, v71
	v_cvt_pk_bf16_f32 v67, v72, v73
	v_cvt_pk_bf16_f32 v68, v68, v69
	v_cvt_pk_bf16_f32 v69, v74, v75
	v_add_u32_e32 v72, 0x80, v144
	global_store_dwordx4 v[80:81], v[66:69], off offset:256
	v_ashrrev_i32_e32 v73, 31, v72
	v_add_u32_e32 v70, 0x90, v144
	v_add_u32_e32 v68, 0xa0, v144
	v_add_u32_e32 v66, 0xb0, v144
	s_cbranch_vccnz .LBB0_481
	v_ashrrev_i32_e32 v71, 31, v70
	v_ashrrev_i32_e32 v69, 31, v68
	v_ashrrev_i32_e32 v67, 31, v66
	v_lshlrev_b64 v[74:75], 6, v[72:73]
	v_lshlrev_b64 v[76:77], 6, v[70:71]
	v_lshlrev_b64 v[82:83], 6, v[68:69]
	v_lshlrev_b64 v[84:85], 6, v[66:67]
	v_lshl_add_u64 v[74:75], v[136:137], 0, v[74:75]
	v_lshl_add_u64 v[78:79], v[136:137], 0, v[76:77]
	v_lshl_add_u64 v[82:83], v[136:137], 0, v[82:83]
	v_lshl_add_u64 v[86:87], v[136:137], 0, v[84:85]
	s_nop 0
	s_nop 0
	s_nop 0
	s_waitcnt vmcnt(8)
	v_mov_b32_e32 v74, v176
	v_mov_b32_e32 v75, v177
	v_mov_b32_e32 v76, v178
	v_mov_b32_e32 v77, v179
	v_mov_b32_e32 v78, v180
	v_mov_b32_e32 v79, v181
	v_mov_b32_e32 v80, v182
	v_mov_b32_e32 v81, v183
	v_mov_b32_e32 v82, v184
	v_mov_b32_e32 v83, v185
	v_mov_b32_e32 v84, v186
	v_mov_b32_e32 v85, v187
	v_mov_b32_e32 v86, v188
	v_mov_b32_e32 v87, v189
	v_mov_b32_e32 v88, v190
	v_mov_b32_e32 v89, v191
	v_mov_b32_e32 v90, v74
	v_mov_b32_e32 v91, v78
	v_mov_b32_e32 v78, v75
	v_cmp_lt_i32_e32 vcc, v218, v213
	v_pk_add_f32 v[74:75], v[90:91], v[78:79]
	v_mov_b32_e32 v78, v76
	v_mov_b32_e32 v79, v80
	v_mov_b32_e32 v80, v77
	v_cndmask_b32_e32 v73, v211, v218, vcc
	v_pk_add_f32 v[76:77], v[78:79], v[80:81]
	v_lshlrev_b32_e32 v92, 2, v73
	v_pk_add_f32 v[74:75], v[74:75], v[76:77]
	ds_bpermute_b32 v76, v92, v74
	ds_bpermute_b32 v77, v92, v75
	v_cmp_lt_i32_e32 vcc, v219, v213
	s_mov_b32 s44, 0x358637bd
	s_mov_b32 s62, 0x3a800000
	v_cndmask_b32_e32 v73, v211, v219, vcc
	v_lshlrev_b32_e32 v93, 2, v73
	s_waitcnt lgkmcnt(0)
	v_pk_add_f32 v[74:75], v[74:75], v[76:77]
	ds_bpermute_b32 v76, v93, v74
	ds_bpermute_b32 v77, v93, v75
	s_mov_b32 s60, 0x45800000
	v_add_f32_e32 v80, v84, v85
	s_waitcnt lgkmcnt(0)
	v_pk_add_f32 v[74:75], v[74:75], v[76:77]
	v_mov_b64_e32 v[76:77], s[44:45]
	v_pk_fma_f32 v[74:75], v[74:75], s[62:63], v[76:77] op_sel_hi:[1,0,0]
	s_nop 0
	v_mul_f32_e32 v73, 0x4b800000, v74
	v_cmp_gt_f32_e64 s[44:45], s53, v74
	v_cmp_gt_f32_e32 vcc, s53, v75
	s_nop 0
	v_cndmask_b32_e64 v73, v74, v73, s[44:45]
	v_rsq_f32_e32 v74, v73
	v_mul_f32_e32 v73, 0x4b800000, v75
	v_cndmask_b32_e32 v73, v75, v73, vcc
	v_rsq_f32_e32 v75, v73
	s_nop 0
	v_pk_mul_f32 v[78:79], v[74:75], s[60:61] op_sel_hi:[1,0]
	s_nop 0
	v_cndmask_b32_e64 v74, v74, v78, s[44:45]
	v_add_f32_e32 v78, v82, v83
	v_mov_b32_e32 v82, v87
	v_mov_b32_e32 v83, v88
	v_mov_b32_e32 v87, v89
	v_pk_add_f32 v[82:83], v[82:83], v[86:87]
	v_cndmask_b32_e32 v73, v75, v79, vcc
	v_mov_b32_e32 v79, v82
	v_mov_b32_e32 v81, v83
	v_pk_add_f32 v[78:79], v[78:79], v[80:81]
	ds_bpermute_b32 v80, v92, v78
	ds_bpermute_b32 v81, v92, v79
	s_waitcnt lgkmcnt(0)
	v_pk_add_f32 v[78:79], v[78:79], v[80:81]
	ds_bpermute_b32 v80, v93, v78
	ds_bpermute_b32 v81, v93, v79
	s_waitcnt lgkmcnt(0)
	v_pk_add_f32 v[78:79], v[78:79], v[80:81]
	s_nop 0
	v_pk_fma_f32 v[76:77], v[78:79], s[62:63], v[76:77] op_sel_hi:[1,0,0]
	s_nop 0
	v_mul_f32_e32 v75, 0x4b800000, v76
	v_cmp_gt_f32_e64 s[44:45], s53, v76
	v_cmp_gt_f32_e32 vcc, s53, v77
	s_nop 0
	v_cndmask_b32_e64 v75, v76, v75, s[44:45]
	v_rsq_f32_e32 v76, v75
	v_mul_f32_e32 v75, 0x4b800000, v77
	v_cndmask_b32_e32 v75, v77, v75, vcc
	v_rsq_f32_e32 v77, v75
	s_nop 0
	v_pk_mul_f32 v[78:79], v[76:77], s[60:61] op_sel_hi:[1,0]
	s_nop 0
	v_cndmask_b32_e64 v76, v76, v78, s[44:45]
	v_cndmask_b32_e32 v75, v77, v79, vcc
	s_cbranch_execnz .LBB0_477

.LBB0_657:
	v_lshl_add_u32 v144, s39, 8, v153
	v_ashrrev_i32_e32 v145, 31, v144
	s_and_b64 vcc, exec, s[46:47]
	v_or_b32_e32 v150, 16, v144
	v_or_b32_e32 v148, 32, v144
	v_or_b32_e32 v146, 48, v144
	s_mov_b32 s39, 0x800000
	s_cbranch_vccz .LBB0_666
	v_ashrrev_i32_e32 v151, 31, v150
	v_lshlrev_b64 v[142:143], 6, v[144:145]
	v_lshlrev_b64 v[160:161], 6, v[150:151]
	v_lshl_add_u64 v[142:143], v[136:137], 0, v[142:143]
	v_lshl_add_u64 v[164:165], v[136:137], 0, v[160:161]
	v_ashrrev_i32_e32 v149, 31, v148
	v_ashrrev_i32_e32 v147, 31, v146
	global_load_dwordx4 v[160:163], v[142:143], off
	s_nop 0
	global_load_dwordx4 v[164:167], v[164:165], off
	v_lshlrev_b64 v[142:143], 6, v[148:149]
	v_lshlrev_b64 v[168:169], 6, v[146:147]
	v_lshl_add_u64 v[142:143], v[136:137], 0, v[142:143]
	v_lshl_add_u64 v[172:173], v[136:137], 0, v[168:169]
	global_load_dwordx4 v[168:171], v[142:143], off
	s_nop 0
	global_load_dwordx4 v[172:175], v[172:173], off
	v_add_u32_e32 v192, 0x80, v144
	v_ashrrev_i32_e32 v193, 31, v192
	v_lshlrev_b64 v[192:193], 6, v[192:193]
	v_lshl_add_u64 v[192:193], v[136:137], 0, v[192:193]
	global_load_dwordx4 v[176:179], v[192:193], off
	global_load_dwordx4 v[180:183], v[192:193], off offset:1024
	global_load_dwordx4 v[184:187], v[192:193], off offset:2048
	global_load_dwordx4 v[188:191], v[192:193], off offset:3072
	v_cmp_lt_i32_e32 vcc, v218, v213
	s_waitcnt vmcnt(0)
	v_mov_b32_e32 v143, v164
	v_mov_b32_e32 v164, v161
	v_cndmask_b32_e32 v142, v211, v218, vcc
	v_cmp_lt_i32_e32 vcc, v219, v213
	v_lshlrev_b32_e32 v152, 2, v142
	v_mov_b32_e32 v161, v166
	v_cndmask_b32_e32 v142, v211, v219, vcc
	v_lshlrev_b32_e32 v156, 2, v142
	v_mov_b32_e32 v142, v160
	v_mov_b32_e32 v160, v162
	v_mov_b32_e32 v166, v163
	v_pk_add_f32 v[142:143], v[142:143], v[164:165]
	v_pk_add_f32 v[160:161], v[160:161], v[166:167]
	s_mov_b32 s44, 0x358637bd
	v_pk_add_f32 v[142:143], v[142:143], v[160:161]
	ds_bpermute_b32 v160, v152, v142
	ds_bpermute_b32 v161, v152, v143
	s_mov_b32 s56, 0x3a800000
	s_mov_b32 s54, 0x45800000
	v_mov_b32_e32 v164, v173
	v_mov_b32_e32 v165, v174
	s_waitcnt lgkmcnt(0)
	v_pk_add_f32 v[142:143], v[142:143], v[160:161]
	ds_bpermute_b32 v160, v156, v142
	ds_bpermute_b32 v161, v156, v143
	v_mov_b32_e32 v173, v175
	v_pk_add_f32 v[164:165], v[164:165], v[172:173]
	s_waitcnt lgkmcnt(0)
	v_pk_add_f32 v[142:143], v[142:143], v[160:161]
	v_mov_b64_e32 v[160:161], s[44:45]
	v_pk_fma_f32 v[142:143], v[142:143], s[56:57], v[160:161] op_sel_hi:[1,0,0]
	s_nop 0
	v_mul_f32_e32 v154, 0x4b800000, v142
	v_cmp_gt_f32_e64 s[44:45], s39, v142
	v_cmp_gt_f32_e32 vcc, s39, v143
	s_nop 0
	v_cndmask_b32_e64 v142, v142, v154, s[44:45]
	v_mul_f32_e32 v154, 0x4b800000, v143
	v_cndmask_b32_e32 v143, v143, v154, vcc
	v_rsq_f32_e32 v142, v142
	v_rsq_f32_e32 v143, v143
	s_nop 0
	v_pk_mul_f32 v[162:163], v[142:143], s[54:55] op_sel_hi:[1,0]
	s_nop 0
	v_cndmask_b32_e64 v158, v142, v162, s[44:45]
	v_cndmask_b32_e32 v154, v143, v163, vcc
	v_add_f32_e32 v142, v168, v169
	v_add_f32_e32 v162, v170, v171
	v_mov_b32_e32 v143, v164
	v_mov_b32_e32 v163, v165
	v_pk_add_f32 v[142:143], v[142:143], v[162:163]
	ds_bpermute_b32 v162, v152, v142
	ds_bpermute_b32 v163, v152, v143
	s_waitcnt lgkmcnt(0)
	v_pk_add_f32 v[142:143], v[142:143], v[162:163]
	ds_bpermute_b32 v162, v156, v142
	ds_bpermute_b32 v163, v156, v143
	s_waitcnt lgkmcnt(0)
	v_pk_add_f32 v[142:143], v[142:143], v[162:163]
	s_nop 0
	v_pk_fma_f32 v[142:143], v[142:143], s[56:57], v[160:161] op_sel_hi:[1,0,0]
	s_nop 0
	v_mul_f32_e32 v152, 0x4b800000, v142
	v_cmp_gt_f32_e64 s[44:45], s39, v142
	v_cmp_gt_f32_e32 vcc, s39, v143
	s_nop 0
	v_cndmask_b32_e64 v142, v142, v152, s[44:45]
	v_mul_f32_e32 v152, 0x4b800000, v143
	v_cndmask_b32_e32 v143, v143, v152, vcc
	v_rsq_f32_e32 v142, v142
	v_rsq_f32_e32 v143, v143
	s_nop 0
	v_pk_mul_f32 v[160:161], v[142:143], s[54:55] op_sel_hi:[1,0]
	s_nop 0
	v_cndmask_b32_e64 v156, v142, v160, s[44:45]
	v_cndmask_b32_e32 v152, v143, v161, vcc
	v_mov_b32_e32 v238, v195
	s_cbranch_execnz .LBB0_660

.LBB0_660:
	v_pk_mul_f32 v[122:123], v[122:123], v[158:159] op_sel_hi:[1,0]
	v_lshl_or_b32 v142, s38, 8, v157
	v_pk_mul_f32 v[128:129], v[128:129], v[158:159] op_sel_hi:[1,0]
	v_pk_mul_f32 v[126:127], v[126:127], v[158:159] op_sel_hi:[1,0]
	v_pk_mul_f32 v[124:125], v[124:125], v[158:159] op_sel_hi:[1,0]
	v_max_f32_e32 v122, 0, v122
	v_max_f32_e32 v123, 0, v123
	v_ashrrev_i32_e32 v143, 31, v142
	v_lshlrev_b64 v[160:161], 13, v[144:145]
	v_max_f32_e32 v126, 0, v126
	v_max_f32_e32 v127, 0, v127
	v_pk_mul_f32 v[162:163], v[122:123], v[122:123]
	v_max_f32_e32 v122, 0, v128
	v_max_f32_e32 v124, 0, v124
	v_max_f32_e32 v123, 0, v129
	v_max_f32_e32 v125, 0, v125
	v_lshl_add_u64 v[160:161], s[28:29], 0, v[160:161]
	v_lshlrev_b64 v[142:143], 1, v[142:143]
	v_pk_mul_f32 v[126:127], v[126:127], v[126:127]
	v_pk_mul_f32 v[128:129], v[122:123], v[122:123]
	v_pk_mul_f32 v[164:165], v[124:125], v[124:125]
	v_pk_mul_f32 v[114:115], v[114:115], v[158:159] op_sel_hi:[1,0]
	v_lshl_add_u64 v[160:161], v[160:161], 0, v[142:143]
	v_cvt_pk_bf16_f32 v122, v126, v127
	v_cvt_pk_bf16_f32 v123, v128, v129
	v_cvt_pk_bf16_f32 v124, v162, v163
	v_cvt_pk_bf16_f32 v125, v164, v165
	v_pk_mul_f32 v[120:121], v[120:121], v[158:159] op_sel_hi:[1,0]
	v_pk_mul_f32 v[118:119], v[118:119], v[158:159] op_sel_hi:[1,0]
	v_pk_mul_f32 v[116:117], v[116:117], v[158:159] op_sel_hi:[1,0]
	v_max_f32_e32 v114, 0, v114
	v_max_f32_e32 v115, 0, v115
	global_store_dwordx4 v[160:161], v[122:125], off
	v_max_f32_e32 v118, 0, v118
	v_max_f32_e32 v119, 0, v119
	v_pk_mul_f32 v[122:123], v[114:115], v[114:115]
	v_max_f32_e32 v114, 0, v120
	v_max_f32_e32 v116, 0, v116
	v_max_f32_e32 v115, 0, v121
	v_max_f32_e32 v117, 0, v117
	v_pk_mul_f32 v[118:119], v[118:119], v[118:119]
	v_pk_mul_f32 v[120:121], v[114:115], v[114:115]
	v_pk_mul_f32 v[124:125], v[116:117], v[116:117]
	v_pk_mul_f32 v[106:107], v[106:107], v[154:155] op_sel_hi:[1,0]
	v_cvt_pk_bf16_f32 v114, v118, v119
	v_cvt_pk_bf16_f32 v115, v120, v121
	v_cvt_pk_bf16_f32 v116, v122, v123
	v_cvt_pk_bf16_f32 v117, v124, v125
	v_pk_mul_f32 v[112:113], v[112:113], v[154:155] op_sel_hi:[1,0]
	v_pk_mul_f32 v[110:111], v[110:111], v[154:155] op_sel_hi:[1,0]
	v_pk_mul_f32 v[108:109], v[108:109], v[154:155] op_sel_hi:[1,0]
	v_max_f32_e32 v106, 0, v106
	v_max_f32_e32 v107, 0, v107
	global_store_dwordx4 v[160:161], v[114:117], off offset:256
	v_max_f32_e32 v110, 0, v110
	v_max_f32_e32 v111, 0, v111
	v_lshlrev_b64 v[114:115], 13, v[150:151]
	v_pk_mul_f32 v[116:117], v[106:107], v[106:107]
	v_max_f32_e32 v106, 0, v112
	v_max_f32_e32 v108, 0, v108
	v_max_f32_e32 v107, 0, v113
	v_max_f32_e32 v109, 0, v109
	v_lshl_add_u64 v[114:115], s[28:29], 0, v[114:115]
	v_pk_mul_f32 v[110:111], v[110:111], v[110:111]
	v_pk_mul_f32 v[112:113], v[106:107], v[106:107]
	v_pk_mul_f32 v[118:119], v[108:109], v[108:109]
	v_pk_mul_f32 v[98:99], v[98:99], v[154:155] op_sel_hi:[1,0]
	v_lshl_add_u64 v[114:115], v[114:115], 0, v[142:143]
	v_cvt_pk_bf16_f32 v106, v110, v111
	v_cvt_pk_bf16_f32 v107, v112, v113
	v_cvt_pk_bf16_f32 v108, v116, v117
	v_cvt_pk_bf16_f32 v109, v118, v119
	v_pk_mul_f32 v[104:105], v[104:105], v[154:155] op_sel_hi:[1,0]
	v_pk_mul_f32 v[102:103], v[102:103], v[154:155] op_sel_hi:[1,0]
	v_pk_mul_f32 v[100:101], v[100:101], v[154:155] op_sel_hi:[1,0]
	v_max_f32_e32 v98, 0, v98
	v_max_f32_e32 v99, 0, v99
	global_store_dwordx4 v[114:115], v[106:109], off
	v_max_f32_e32 v102, 0, v102
	v_max_f32_e32 v103, 0, v103
	v_pk_mul_f32 v[106:107], v[98:99], v[98:99]
	v_max_f32_e32 v98, 0, v104
	v_max_f32_e32 v100, 0, v100
	v_max_f32_e32 v99, 0, v105
	v_max_f32_e32 v101, 0, v101
	v_pk_mul_f32 v[102:103], v[102:103], v[102:103]
	v_pk_mul_f32 v[104:105], v[98:99], v[98:99]
	v_pk_mul_f32 v[108:109], v[100:101], v[100:101]
	v_pk_mul_f32 v[90:91], v[90:91], v[156:157] op_sel_hi:[1,0]
	v_cvt_pk_bf16_f32 v98, v102, v103
	v_cvt_pk_bf16_f32 v99, v104, v105
	v_cvt_pk_bf16_f32 v100, v106, v107
	v_cvt_pk_bf16_f32 v101, v108, v109
	v_pk_mul_f32 v[96:97], v[96:97], v[156:157] op_sel_hi:[1,0]
	v_pk_mul_f32 v[94:95], v[94:95], v[156:157] op_sel_hi:[1,0]
	v_pk_mul_f32 v[92:93], v[92:93], v[156:157] op_sel_hi:[1,0]
	v_max_f32_e32 v90, 0, v90
	v_max_f32_e32 v91, 0, v91
	global_store_dwordx4 v[114:115], v[98:101], off offset:256
	v_max_f32_e32 v94, 0, v94
	v_max_f32_e32 v95, 0, v95
	v_lshlrev_b64 v[98:99], 13, v[148:149]
	v_pk_mul_f32 v[100:101], v[90:91], v[90:91]
	v_max_f32_e32 v90, 0, v96
	v_max_f32_e32 v92, 0, v92
	v_max_f32_e32 v91, 0, v97
	v_max_f32_e32 v93, 0, v93
	v_lshl_add_u64 v[98:99], s[28:29], 0, v[98:99]
	v_pk_mul_f32 v[94:95], v[94:95], v[94:95]
	v_pk_mul_f32 v[96:97], v[90:91], v[90:91]
	v_pk_mul_f32 v[102:103], v[92:93], v[92:93]
	v_pk_mul_f32 v[82:83], v[82:83], v[156:157] op_sel_hi:[1,0]
	v_lshl_add_u64 v[98:99], v[98:99], 0, v[142:143]
	v_cvt_pk_bf16_f32 v90, v94, v95
	v_cvt_pk_bf16_f32 v91, v96, v97
	v_cvt_pk_bf16_f32 v92, v100, v101
	v_cvt_pk_bf16_f32 v93, v102, v103
	v_pk_mul_f32 v[88:89], v[88:89], v[156:157] op_sel_hi:[1,0]
	v_pk_mul_f32 v[86:87], v[86:87], v[156:157] op_sel_hi:[1,0]
	v_pk_mul_f32 v[84:85], v[84:85], v[156:157] op_sel_hi:[1,0]
	v_max_f32_e32 v82, 0, v82
	v_max_f32_e32 v83, 0, v83
	global_store_dwordx4 v[98:99], v[90:93], off
	v_max_f32_e32 v86, 0, v86
	v_max_f32_e32 v87, 0, v87
	v_pk_mul_f32 v[90:91], v[82:83], v[82:83]
	v_max_f32_e32 v82, 0, v88
	v_max_f32_e32 v84, 0, v84
	v_max_f32_e32 v83, 0, v89
	v_max_f32_e32 v85, 0, v85
	v_pk_mul_f32 v[86:87], v[86:87], v[86:87]
	v_pk_mul_f32 v[88:89], v[82:83], v[82:83]
	v_pk_mul_f32 v[92:93], v[84:85], v[84:85]
	v_pk_mul_f32 v[74:75], v[74:75], v[152:153] op_sel_hi:[1,0]
	v_cvt_pk_bf16_f32 v82, v86, v87
	v_cvt_pk_bf16_f32 v83, v88, v89
	v_cvt_pk_bf16_f32 v84, v90, v91
	v_cvt_pk_bf16_f32 v85, v92, v93
	v_pk_mul_f32 v[80:81], v[80:81], v[152:153] op_sel_hi:[1,0]
	v_pk_mul_f32 v[78:79], v[78:79], v[152:153] op_sel_hi:[1,0]
	v_pk_mul_f32 v[76:77], v[76:77], v[152:153] op_sel_hi:[1,0]
	v_max_f32_e32 v74, 0, v74
	v_max_f32_e32 v75, 0, v75
	global_store_dwordx4 v[98:99], v[82:85], off offset:256
	v_max_f32_e32 v78, 0, v78
	v_max_f32_e32 v79, 0, v79
	v_lshlrev_b64 v[82:83], 13, v[146:147]
	v_pk_mul_f32 v[84:85], v[74:75], v[74:75]
	v_max_f32_e32 v74, 0, v80
	v_max_f32_e32 v76, 0, v76
	v_max_f32_e32 v75, 0, v81
	v_max_f32_e32 v77, 0, v77
	v_lshl_add_u64 v[82:83], s[28:29], 0, v[82:83]
	v_pk_mul_f32 v[78:79], v[78:79], v[78:79]
	v_pk_mul_f32 v[80:81], v[74:75], v[74:75]
	v_pk_mul_f32 v[86:87], v[76:77], v[76:77]
	v_pk_mul_f32 v[66:67], v[66:67], v[152:153] op_sel_hi:[1,0]
	v_lshl_add_u64 v[82:83], v[82:83], 0, v[142:143]
	v_cvt_pk_bf16_f32 v74, v78, v79
	v_cvt_pk_bf16_f32 v75, v80, v81
	v_cvt_pk_bf16_f32 v76, v84, v85
	v_cvt_pk_bf16_f32 v77, v86, v87
	v_pk_mul_f32 v[72:73], v[72:73], v[152:153] op_sel_hi:[1,0]
	v_pk_mul_f32 v[70:71], v[70:71], v[152:153] op_sel_hi:[1,0]
	v_pk_mul_f32 v[68:69], v[68:69], v[152:153] op_sel_hi:[1,0]
	v_max_f32_e32 v66, 0, v66
	v_max_f32_e32 v67, 0, v67
	global_store_dwordx4 v[82:83], v[74:77], off
	v_max_f32_e32 v70, 0, v70
	v_max_f32_e32 v71, 0, v71
	v_pk_mul_f32 v[74:75], v[66:67], v[66:67]
	v_max_f32_e32 v66, 0, v72
	v_max_f32_e32 v68, 0, v68
	v_max_f32_e32 v67, 0, v73
	v_max_f32_e32 v69, 0, v69
	v_pk_mul_f32 v[70:71], v[70:71], v[70:71]
	v_pk_mul_f32 v[72:73], v[66:67], v[66:67]
	v_pk_mul_f32 v[76:77], v[68:69], v[68:69]
	v_cvt_pk_bf16_f32 v66, v70, v71
	v_cvt_pk_bf16_f32 v67, v72, v73
	v_cvt_pk_bf16_f32 v68, v74, v75
	v_cvt_pk_bf16_f32 v69, v76, v77
	v_add_u32_e32 v74, 0x80, v144
	global_store_dwordx4 v[82:83], v[66:69], off offset:256
	v_ashrrev_i32_e32 v75, 31, v74
	s_andn2_b64 vcc, exec, s[46:47]
	v_add_u32_e32 v70, 0x90, v144
	v_add_u32_e32 v68, 0xa0, v144
	v_add_u32_e32 v66, 0xb0, v144
	s_cbranch_vccnz .LBB0_667
	v_ashrrev_i32_e32 v71, 31, v70
	v_lshlrev_b64 v[72:73], 6, v[74:75]
	v_lshlrev_b64 v[76:77], 6, v[70:71]
	v_lshl_add_u64 v[72:73], v[136:137], 0, v[72:73]
	v_lshl_add_u64 v[80:81], v[136:137], 0, v[76:77]
	v_ashrrev_i32_e32 v69, 31, v68
	v_ashrrev_i32_e32 v67, 31, v66
	s_nop 0
	v_lshlrev_b64 v[72:73], 6, v[68:69]
	v_lshlrev_b64 v[84:85], 6, v[66:67]
	v_lshl_add_u64 v[72:73], v[136:137], 0, v[72:73]
	v_lshl_add_u64 v[88:89], v[136:137], 0, v[84:85]
	s_nop 0
	v_cmp_lt_i32_e32 vcc, v218, v213
	s_waitcnt vmcnt(8)
	v_mov_b32_e32 v76, v176
	v_mov_b32_e32 v77, v177
	v_mov_b32_e32 v78, v178
	v_mov_b32_e32 v79, v179
	v_mov_b32_e32 v80, v180
	v_mov_b32_e32 v81, v181
	v_mov_b32_e32 v82, v182
	v_mov_b32_e32 v83, v183
	v_mov_b32_e32 v84, v184
	v_mov_b32_e32 v85, v185
	v_mov_b32_e32 v86, v186
	v_mov_b32_e32 v87, v187
	v_mov_b32_e32 v88, v188
	v_mov_b32_e32 v89, v189
	v_mov_b32_e32 v90, v190
	v_mov_b32_e32 v91, v191
	v_mov_b32_e32 v73, v80
	v_mov_b32_e32 v80, v77
	v_cndmask_b32_e32 v72, v211, v218, vcc
	v_cmp_lt_i32_e32 vcc, v219, v213
	v_lshlrev_b32_e32 v92, 2, v72
	v_mov_b32_e32 v77, v82
	v_cndmask_b32_e32 v72, v211, v219, vcc
	v_lshlrev_b32_e32 v93, 2, v72
	v_mov_b32_e32 v72, v76
	v_mov_b32_e32 v76, v78
	v_mov_b32_e32 v82, v79
	v_pk_add_f32 v[72:73], v[72:73], v[80:81]
	v_pk_add_f32 v[76:77], v[76:77], v[82:83]
	s_mov_b32 s38, 0x358637bd
	v_pk_add_f32 v[72:73], v[72:73], v[76:77]
	ds_bpermute_b32 v76, v92, v72
	ds_bpermute_b32 v77, v92, v73
	v_mov_b64_e32 v[78:79], s[38:39]
	s_mov_b32 s54, 0x3a800000
	s_mov_b32 s38, 0x45800000
	v_add_f32_e32 v82, v86, v87
	s_waitcnt lgkmcnt(0)
	v_pk_add_f32 v[72:73], v[72:73], v[76:77]
	ds_bpermute_b32 v76, v93, v72
	ds_bpermute_b32 v77, v93, v73
	s_waitcnt lgkmcnt(0)
	v_pk_add_f32 v[72:73], v[72:73], v[76:77]
	s_nop 0
	v_pk_fma_f32 v[72:73], v[72:73], s[54:55], v[78:79] op_sel_hi:[1,0,0]
	s_nop 0
	v_mul_f32_e32 v76, 0x4b800000, v72
	v_cmp_gt_f32_e64 s[44:45], s39, v72
	v_cmp_gt_f32_e32 vcc, s39, v73
	s_nop 0
	v_cndmask_b32_e64 v72, v72, v76, s[44:45]
	v_mul_f32_e32 v76, 0x4b800000, v73
	v_cndmask_b32_e32 v73, v73, v76, vcc
	v_rsq_f32_e32 v72, v72
	v_rsq_f32_e32 v73, v73
	s_nop 0
	v_pk_mul_f32 v[76:77], v[72:73], s[38:39] op_sel_hi:[1,0]
	s_nop 0
	v_cndmask_b32_e64 v80, v72, v76, s[44:45]
	v_add_f32_e32 v72, v84, v85
	v_mov_b32_e32 v84, v89
	v_mov_b32_e32 v85, v90
	v_mov_b32_e32 v89, v91
	v_pk_add_f32 v[84:85], v[84:85], v[88:89]
	v_cndmask_b32_e32 v76, v73, v77, vcc
	v_mov_b32_e32 v73, v84
	v_mov_b32_e32 v83, v85
	v_pk_add_f32 v[72:73], v[72:73], v[82:83]
	ds_bpermute_b32 v82, v92, v72
	ds_bpermute_b32 v83, v92, v73
	s_waitcnt lgkmcnt(0)
	v_pk_add_f32 v[72:73], v[72:73], v[82:83]
	ds_bpermute_b32 v82, v93, v72
	ds_bpermute_b32 v83, v93, v73
	s_waitcnt lgkmcnt(0)
	v_pk_add_f32 v[72:73], v[72:73], v[82:83]
	s_nop 0
	v_pk_fma_f32 v[72:73], v[72:73], s[54:55], v[78:79] op_sel_hi:[1,0,0]
	s_nop 0
	v_mul_f32_e32 v77, 0x4b800000, v72
	v_cmp_gt_f32_e64 s[44:45], s39, v72
	v_cmp_gt_f32_e32 vcc, s39, v73
	s_nop 0
	v_cndmask_b32_e64 v72, v72, v77, s[44:45]
	v_mul_f32_e32 v77, 0x4b800000, v73
	v_cndmask_b32_e32 v73, v73, v77, vcc
	v_rsq_f32_e32 v72, v72
	v_rsq_f32_e32 v73, v73
	s_nop 0
	v_pk_mul_f32 v[78:79], v[72:73], s[38:39] op_sel_hi:[1,0]
	s_nop 0
	v_cndmask_b32_e64 v78, v72, v78, s[44:45]
	v_cndmask_b32_e32 v72, v73, v79, vcc
	s_cbranch_execnz .LBB0_663
